# phase 2 pair loop: LDS-DMA addresses as SGPR base plus precomputed lane offsets, scalar address arithmetic hoisted in front of the loop-top wait+barrier (same as phase 19)
# baseline (speedup 1.0000x reference)
; #define GAS __attribute__((address_space(1)))
; #define ATT_ISSUE2(p_, st_) do { LAS unsigned char* sp_ = lds + (st_) * STG2; const int ta_ = dual ? (p_) : 2 * (p_), tb_ = dual ? (p_) : 2 * (p_) + 1; ATT_ISSUE1(u, ta_, sp_); ATT_ISSUEM(ta_, sp_ + 2 * STAGEB); \
;         if (dual || tb_ < u.ntiles) { ATT_ISSUE1(ub, tb_, sp_ + STAGEB); ATT_ISSUEM(tb_, sp_ + 2 * STAGEB + MSKB); } } while (0)
;     ...
;     { const bf16* Q = (const bf16*)(F.ws + (LAYER == 0 ? WS_QA : WS_QB)) + (size_t)(active ? qrow : u.qrow0) * D + hcol + koff + 8 * hi;
; #pragma unroll
;       for (int ks = 0; ks < NKS; ++ks) qf[ks] = *(const GAS bf16x8*)(Q + 16 * ks); }
;     ...
;         const AttnUnit& ub = dual ? u2 : u;
;         const int npairs = dual ? u.ntiles : (u.ntiles + 1) >> 1, p0 = dual ? T0 : T0 >> 1;
;         ATT_ISSUE2(p0, p0 & 1);
.LBB0_575:
	v_mov_b32_e32 v171, v0
	s_add_i32 s1, s87, s60
	v_and_b32_e32 v4, 31, v171
	v_add_u32_e32 v168, s1, v4
	v_ashrrev_i32_e32 v169, 31, v168
	v_lshlrev_b64 v[172:173], 12, v[168:169]
	v_lshl_add_u64 v[6:7], s[20:21], 0, v[172:173]
	s_lshl_b32 s10, s85, 8
	v_lshl_add_u64 v[6:7], v[6:7], 0, s[10:11]
	s_lshl_b32 s2, s47, 1
	s_mov_b32 s3, s11
	v_lshl_add_u64 v[6:7], v[6:7], 0, s[2:3]
	s_lshl_b32 s3, s0, 11
	s_lshl_b32 s0, s74, 6
	s_add_i32 s0, s3, s0
	s_ashr_i32 s1, s0, 31
	s_lshl_b64 s[4:5], s[0:1], 12
	s_or_b32 s2, s74, 1
	s_or_b32 s1, s4, s10
	v_bfe_u32 v8, v171, 4, 2
	v_bfe_u32 v185, v171, 5, 1
	s_add_u32 s6, s56, s1
	v_or_b32_e32 v2, s52, v8
	v_lshlrev_b32_e32 v166, 4, v185
	v_mov_b32_e32 v167, v3
	s_addc_u32 s7, s57, s5
	v_lshlrev_b64 v[174:175], 12, v[2:3]
	v_bitop3_b32 v2, v8, v171, s52 bitop3:0x36
	v_lshl_add_u64 v[6:7], v[6:7], 0, v[166:167]
	s_add_u32 s8, s49, s1
	v_lshlrev_b32_e32 v2, 4, v2
	global_load_dwordx4 v[132:135], v[6:7], off
	global_load_dwordx4 v[136:139], v[6:7], off offset:32
	global_load_dwordx4 v[140:143], v[6:7], off offset:64
	global_load_dwordx4 v[144:147], v[6:7], off offset:96
	v_and_b32_e32 v5, 15, v171
	s_addc_u32 s9, s50, s5
	v_lshlrev_b32_e32 v9, 2, v8
	v_lshl_add_u64 v[6:7], s[6:7], 0, v[174:175]
	v_and_b32_e32 v2, 0xf0, v2
	s_add_i32 s1, s61, 0
	v_lshl_add_u64 v[6:7], v[6:7], 0, v[2:3]
	s_mov_b32 m0, s1
	v_bitop3_b32 v10, v9, v5, s62 bitop3:0x36
	global_load_lds_dwordx4 v[6:7], off
	v_lshl_add_u64 v[6:7], s[8:9], 0, v[174:175]
	v_lshlrev_b32_e32 v176, 4, v10
	v_mov_b32_e32 v177, v3
	v_lshl_add_u64 v[6:7], v[6:7], 0, v[176:177]
	s_add_i32 m0, s1, 0x4000
	v_mov_b32_e32 v181, v3
	global_load_lds_dwordx4 v[6:7], off
	v_or_b32_e32 v6, s53, v8
	v_mov_b32_e32 v7, v3
	v_bitop3_b32 v8, v8, v171, s53 bitop3:0x36
	v_lshlrev_b64 v[178:179], 12, v[6:7]
	v_lshlrev_b32_e32 v8, 4, v8
	v_lshl_add_u64 v[6:7], s[6:7], 0, v[178:179]
	v_and_b32_e32 v180, 0xf0, v8
	s_add_i32 s4, s63, 0
	v_lshl_add_u64 v[6:7], v[6:7], 0, v[180:181]
	s_mov_b32 m0, s4
	v_bitop3_b32 v8, v9, v5, s64 bitop3:0x36
	global_load_lds_dwordx4 v[6:7], off
	v_lshl_add_u64 v[6:7], s[8:9], 0, v[178:179]
	v_lshlrev_b32_e32 v182, 4, v8
	v_mov_b32_e32 v183, v3
	v_lshl_add_u64 v[6:7], v[6:7], 0, v[182:183]
	s_add_i32 m0, s4, 0x4000
	v_add_u32_e32 v248, v174, v2
	v_add_u32_e32 v249, v174, v176
	v_add_u32_e32 v250, v178, v180
	v_add_u32_e32 v251, v178, v182
	s_cmp_ge_u32 s2, s75
	global_load_lds_dwordx4 v[6:7], off
	s_cbranch_scc1 .LBB0_577
	s_lshl_b32 s2, s2, 6
	s_add_i32 s6, s3, s2
	s_ashr_i32 s7, s6, 31
	s_lshl_b64 s[6:7], s[6:7], 12
	s_or_b64 s[6:7], s[6:7], s[10:11]
	s_add_u32 s8, s56, s6
	s_addc_u32 s9, s57, s7
	s_add_u32 s6, s49, s6
	v_lshl_add_u64 v[6:7], s[8:9], 0, v[174:175]
	s_mov_b32 m0, s70
	s_addc_u32 s7, s50, s7
	v_lshl_add_u64 v[6:7], v[6:7], 0, v[2:3]
	global_load_lds_dwordx4 v[6:7], off
	v_lshl_add_u64 v[6:7], s[6:7], 0, v[174:175]
	v_lshl_add_u64 v[6:7], v[6:7], 0, v[176:177]
	s_add_i32 m0, s1, 0xc000
	s_nop 0
	global_load_lds_dwordx4 v[6:7], off
	v_lshl_add_u64 v[6:7], s[8:9], 0, v[178:179]
	v_lshl_add_u64 v[6:7], v[6:7], 0, v[180:181]
	s_add_i32 m0, s4, 0x8000
	s_nop 0
	global_load_lds_dwordx4 v[6:7], off
	v_lshl_add_u64 v[6:7], s[6:7], 0, v[178:179]
	v_lshl_add_u64 v[6:7], v[6:7], 0, v[182:183]
	s_add_i32 m0, s4, 0xc000
	s_nop 0
	global_load_lds_dwordx4 v[6:7], off

; #define ATT_ISSUE2(p_, st_) do { LAS unsigned char* sp_ = lds + (st_) * STG2; const int ta_ = dual ? (p_) : 2 * (p_), tb_ = dual ? (p_) : 2 * (p_) + 1; ATT_ISSUE1(u, ta_, sp_); ATT_ISSUEM(ta_, sp_ + 2 * STAGEB); \
;         if (dual || tb_ < u.ntiles) { ATT_ISSUE1(ub, tb_, sp_ + STAGEB); ATT_ISSUEM(tb_, sp_ + 2 * STAGEB + MSKB); } } while (0)
;     ...
;         const AttnUnit& ub = dual ? u2 : u;
;         const int npairs = dual ? u.ntiles : (u.ntiles + 1) >> 1, p0 = dual ? T0 : T0 >> 1;
;         ATT_ISSUE2(p0, p0 & 1);
;         for (int p = p0; p < npairs; ++p) {
;             asm volatile("s_waitcnt vmcnt(0)" ::: "memory");
;             __builtin_amdgcn_s_barrier(); asm volatile("" ::: "memory");
;             if (p + 1 < npairs) ATT_ISSUE2(p + 1, (p + 1) & 1);
.LBB0_579:
	s_add_i32 s27, s2, 1
	s_cmp_ge_u32 s27, s8
	s_cselect_b64 s[6:7], -1, 0
	s_and_b64 vcc, exec, s[6:7]
	s_cbranch_vccnz .Lpb2_done
	s_bitcmp1_b32 s27, 0
	s_cselect_b32 s1, 0x10400, 0
	s_ashr_i32 s5, s4, 31
	s_lshl_b64 s[28:29], s[4:5], 12
	s_add_i32 s1, s1, 0
	s_add_i32 s34, s74, 3
	s_or_b64 s[28:29], s[28:29], s[10:11]
	s_add_u32 s30, s56, s28
	s_addc_u32 s31, s57, s29
	s_add_u32 s28, s49, s28
	s_addc_u32 s29, s50, s29
	s_add_i32 s3, s1, s61
	s_add_i32 s5, s1, s63
	s_ashr_i32 s1, s0, 31
	s_lshl_b64 s[100:101], s[0:1], 12
	s_or_b64 s[100:101], s[100:101], s[10:11]
	s_add_u32 s98, s56, s100
	s_addc_u32 s99, s57, s101
	s_add_u32 s100, s49, s100
	s_addc_u32 s101, s50, s101
.Lpb2_done:
	v_readlane_b32 s1, v254, 11
	s_waitcnt vmcnt(0)
	s_barrier
	s_cmp_lt_u32 s1, 4
	s_cbranch_scc1 .Lstag_579
	s_sleep 8
	s_setprio 1
.Lstag_579:
	s_and_b64 vcc, exec, s[6:7]
	s_cbranch_vccnz .LBB0_582
	s_mov_b32 m0, s3
	s_nop 0
	global_load_lds_dwordx4 v248, s[30:31]
	s_add_i32 m0, s3, 0x4000
	s_nop 0
	global_load_lds_dwordx4 v249, s[28:29]
	s_mov_b32 m0, s5
	s_nop 0
	global_load_lds_dwordx4 v250, s[30:31]
	s_add_i32 m0, s5, 0x4000
	s_cmp_ge_u32 s34, s75
	global_load_lds_dwordx4 v251, s[28:29]
	s_cbranch_scc1 .LBB0_582
	s_add_i32 m0, s3, 0x8000
	s_nop 0
	global_load_lds_dwordx4 v248, s[98:99]
	s_add_i32 m0, s3, 0xc000
	s_nop 0
	global_load_lds_dwordx4 v249, s[100:101]
	s_add_i32 m0, s5, 0x8000
	s_nop 0
	global_load_lds_dwordx4 v250, s[98:99]
	s_add_i32 m0, s5, 0xc000
	s_nop 0
	global_load_lds_dwordx4 v251, s[100:101]
